# B28+rows7+rows10 + PLE GEMM units rebalanced in P3b: 3-sample WGs none, pool WGs 4, scan WGs 2 each before their scan
# speedup vs baseline: 1.0102x; 1.0102x over previous
.LBB0_935:
	s_or_b64 exec, exec, s[0:1]
	v_readlane_b32 s64, v250, 10
	v_readlane_b32 s65, v250, 11
	s_waitcnt lgkmcnt(0)
	s_barrier
	s_cmpk_gt_i32 s66, 0x5f
	v_mbcnt_lo_u32_b32 v204, -1, 0
	v_mbcnt_hi_u32_b32 v204, -1, v204
	s_mov_b64 s[0:1], -1
	s_cbranch_scc1 .Lp3_nonscan
	s_cmpk_lg_i32 s88, 0x100
	s_cbranch_scc1 .LBB0_1060
	s_mov_b32 s98, 1
	s_movk_i32 s7, 0x60
	s_add_i32 s40, s66, 0x180
	s_movk_i32 s100, 0x240
	s_branch .LBB0_961
.Lp3_scan_resume:
	s_mov_b64 s[0:1], -1
	s_branch .LBB0_1060
.Lp3_nonscan:
	s_mov_b32 s98, 0
	s_add_i32 s7, s88, 0xffffffa0
	s_lshl_b32 s6, s7, 3
	s_abs_i32 s0, s6
	v_cvt_f32_u32_e32 v0, s0
	s_sub_i32 s1, 0, s0
	s_add_i32 s40, s66, 0xffffffa0
	v_rcp_iflag_f32_e32 v0, v0
	s_nop 0
	v_mul_f32_e32 v0, 0x4f7ffffe, v0
	v_cvt_u32_f32_e32 v0, v0
	s_nop 0
	v_readfirstlane_b32 s8, v0
	s_mul_i32 s1, s1, s8
	s_mul_hi_u32 s1, s8, s1
	s_add_i32 s8, s8, s1
	s_mul_hi_u32 s1, s8, 0xc00
	s_mul_i32 s1, s1, s0
	s_sub_i32 s1, 0xc00, s1
	s_sub_i32 s8, s1, s0
	s_cmp_ge_u32 s1, s0
	s_cselect_b32 s1, s8, s1
	s_sub_i32 s8, s1, s0
	s_cmp_ge_u32 s1, s0
	s_cselect_b32 s0, s8, s1
	s_lshr_b32 s10, s0, 3
	s_cmp_lg_u32 s0, 0
	s_cselect_b64 s[0:1], -1, 0
	s_sub_i32 s11, s7, s10
	s_cmp_gt_i32 s11, 63
	s_cselect_b64 s[8:9], -1, 0
	s_and_b64 s[0:1], s[0:1], s[8:9]
	s_and_b64 s[0:1], s[0:1], exec
	s_cselect_b32 s41, s11, s7
	s_cmp_lg_u32 s41, s7
	s_cselect_b32 s0, s10, 0
	s_sub_i32 s42, s40, s0
	s_cmp_lt_i32 s42, 0
	s_cbranch_scc1 .LBB0_961
	v_mbcnt_lo_u32_b32 v8, -1, 0
	v_mbcnt_hi_u32_b32 v8, -1, v8
	s_cmpk_gt_u32 s42, 0x8f
	s_cbranch_scc1 .LBB0_961
	v_lshl_add_u32 v0, v8, 4, s93
	v_add_u32_e32 v1, 0x2000, v0
	v_ashrrev_i32_e32 v2, 31, v1
	v_lshrrev_b32_e32 v2, 22, v2
	v_add_u32_e32 v2, v1, v2
	v_ashrrev_i32_e32 v2, 10, v2
	v_mul_i32_i24_e32 v3, 0x400, v2
	v_sub_u32_e32 v1, v1, v3
	v_lshrrev_b32_e32 v3, 4, v1
	v_bitop3_b32 v1, v3, v1, 32 bitop3:0x6c
	v_ashrrev_i32_e32 v3, 31, v1
	v_lshrrev_b32_e32 v3, 26, v3
	v_add_u32_e32 v3, v1, v3
	v_ashrrev_i32_e32 v4, 6, v3
	v_and_b32_e32 v3, 0xffc0, v3
	v_sub_u32_e32 v1, v1, v3
	v_lshlrev_b32_e32 v5, 3, v2
	v_lshrrev_b16_e32 v3, 7, v1
	v_and_b32_e32 v5, -16, v5
	v_and_b32_e32 v3, 1, v3
	v_add_u32_e32 v5, v4, v5
	v_add_u16_e32 v1, v1, v3
	v_mov_b32_e32 v3, 1
	v_and_b32_e32 v4, 3, v4
	s_mov_b32 s10, 0x7fffe0
	v_lshrrev_b32_e32 v6, 2, v5
	v_lshlrev_b32_e32 v7, 1, v5
	v_lshlrev_b32_e32 v2, 5, v2
	v_ashrrev_i16_sdwa v1, v3, sext(v1) dst_sel:DWORD dst_unused:UNUSED_PAD src0_sel:DWORD src1_sel:BYTE_0
	v_and_or_b32 v4, v5, s10, v4
	v_and_b32_e32 v6, 4, v6
	v_and_b32_e32 v7, 24, v7
	v_and_b32_e32 v2, 32, v2
	v_bfe_i32 v1, v1, 0, 16
	v_or3_b32 v4, v4, v6, v7
	v_add_lshl_u32 v1, v2, v1, 1
	v_lshl_add_u32 v138, v4, 9, v1
	v_lshl_add_u32 v140, v5, 11, v1
	v_ashrrev_i32_e32 v1, 31, v0
	v_lshrrev_b32_e32 v1, 22, v1
	v_add_u32_e32 v1, v0, v1
	v_ashrrev_i32_e32 v1, 10, v1
	v_mul_i32_i24_e32 v2, 0x400, v1
	v_sub_u32_e32 v0, v0, v2
	s_load_dwordx2 s[0:1], s[64:65], 0xc0
	s_load_dwordx2 s[8:9], s[64:65], 0x48
	v_lshrrev_b32_e32 v2, 4, v0
	v_bitop3_b32 v0, v2, v0, 32 bitop3:0x6c
	v_ashrrev_i32_e32 v2, 31, v0
	v_lshrrev_b32_e32 v2, 26, v2
	s_waitcnt lgkmcnt(0)
	s_add_u32 s43, s0, 0x2ea00000
	v_add_u32_e32 v2, v0, v2
	v_lshlrev_b32_e32 v5, 3, v1
	s_addc_u32 s44, s1, 0
	v_ashrrev_i32_e32 v4, 6, v2
	v_and_b32_e32 v5, -16, v5
	s_add_u32 s45, s0, 0x1f700000
	v_add_u32_e32 v5, v4, v5
	v_and_b32_e32 v4, 3, v4
	s_addc_u32 s46, s1, 0
	v_and_or_b32 v4, v5, s10, v4
	s_and_b32 s10, s42, 7
	s_lshr_b32 s11, s42, 3
	s_mul_i32 s10, s10, 18
	s_add_i32 s10, s10, s11
	v_and_b32_e32 v2, 0xc0, v2
	s_lshr_b32 s11, s10, 2
	v_sub_u32_e32 v0, v0, v2
	s_and_b32 s14, s11, 56
	v_lshlrev_b32_e32 v1, 5, v1
	v_ashrrev_i16_sdwa v0, v3, sext(v0) dst_sel:DWORD dst_unused:UNUSED_PAD src0_sel:DWORD src1_sel:BYTE_0
	s_sub_i32 s11, 36, s14
	v_and_b32_e32 v1, 32, v1
	v_bfe_i32 v0, v0, 0, 16
	s_min_u32 s15, s11, 8
	v_add_lshl_u32 v0, v1, v0, 1
	v_cvt_f32_ubyte0_e32 v1, s15
	v_rcp_iflag_f32_e32 v2, v1
	s_and_b32 s16, s10, 31
	v_lshrrev_b32_e32 v6, 2, v5
	v_lshlrev_b32_e32 v7, 1, v5
	v_cvt_f32_ubyte0_e32 v3, s16
	v_and_b32_e32 v6, 4, v6
	v_and_b32_e32 v7, 24, v7
	v_mul_f32_e32 v2, v3, v2
	v_or3_b32 v4, v4, v6, v7
	v_trunc_f32_e32 v2, v2
	v_lshl_add_u32 v142, v4, 9, v0
	v_cvt_u32_f32_e32 v4, v2
	v_lshl_add_u32 v144, v5, 11, v0
	v_fma_f32 v0, -v2, v1, v3
	v_cmp_ge_f32_e64 s[10:11], |v0|, v1
	v_readfirstlane_b32 s17, v4
	s_cmp_lg_u64 s[10:11], 0
	s_addc_u32 s10, s17, 0
	s_mul_i32 s11, s10, s15
	s_sub_i32 s11, s16, s11
	s_and_b32 s11, s11, 0xff
	s_add_i32 s57, s14, s11
	s_and_b32 s58, s10, 0xff
	s_lshl_b32 s11, s57, 19
	s_lshl_b32 s14, s58, 9
	s_lshl_b32 s10, s58, 17
	s_add_u32 s34, s45, s10
	s_addc_u32 s35, s46, 0
	s_add_i32 s47, s93, 0
	s_add_i32 m0, s47, 0x10000
	v_mov_b32_e32 v143, 0
	global_load_lds_dwordx4 v142, s[34:35]
	s_add_i32 m0, s47, 0x12000
	s_add_u32 s15, s43, s11
	s_addc_u32 s16, s44, 0
	s_add_u32 s10, s34, 0x10000
	global_load_lds_dwordx4 v138, s[34:35]
	s_addc_u32 s11, s35, 0
	s_add_i32 m0, s47, 0x14000
	v_readlane_b32 s4, v250, 21
	global_load_lds_dwordx4 v142, s[10:11]
	s_add_i32 m0, s47, 0x16000
	s_add_u32 s36, s15, s14
	s_addc_u32 s37, s16, 0
	s_add_i32 s48, s47, 0x2000
	global_load_lds_dwordx4 v138, s[10:11]
	s_mov_b32 m0, s47
	s_add_u32 s10, s36, 0x40000
	global_load_lds_dwordx4 v144, s[36:37]
	s_mov_b32 m0, s48
	s_addc_u32 s11, s37, 0
	s_add_i32 s49, s47, 0x4000
	global_load_lds_dwordx4 v140, s[36:37]
	s_mov_b32 m0, s49
	s_add_i32 s50, s47, 0x6000
	global_load_lds_dwordx4 v144, s[10:11]
	s_mov_b32 m0, s50
	v_mov_b32_e32 v139, v143
	global_load_lds_dwordx4 v140, s[10:11]
	v_mov_b32_e32 v145, v143
	v_mov_b32_e32 v141, v143
	v_readlane_b32 s5, v250, 22
	s_mov_b32 s51, 0
	v_lshl_add_u64 v[6:7], s[34:35], 0, v[142:143]
	v_lshl_add_u64 v[4:5], s[34:35], 0, v[138:139]
	v_lshl_add_u64 v[0:1], s[36:37], 0, v[144:145]
	s_and_b64 vcc, exec, s[4:5]
	v_lshl_add_u64 v[2:3], s[36:37], 0, v[140:141]
	s_cbranch_vccnz .LBB0_940
	s_barrier

.LBB0_961:
	s_cmpk_gt_i32 s66, 0x29f
	v_mbcnt_lo_u32_b32 v8, -1, 0
	v_mbcnt_hi_u32_b32 v8, -1, v8
	s_nop 0
	s_cbranch_scc1 .LBB0_978
	s_cmp_eq_u32 s98, 1
	s_cbranch_scc1 .Lple_go
	s_mov_b32 s99, s40
	s_movk_i32 s100, 0x240
	s_cmpk_lg_i32 s88, 0x100
	s_cbranch_scc1 .Lple_go
	s_cmpk_lt_i32 s40, 64
	s_cbranch_scc1 .LBB0_978
	s_sub_i32 s40, s40, 64
	s_movk_i32 s7, 0x60
	s_movk_i32 s100, 0x180
.Lple_go:
	s_add_i32 s101, s100, -1
	v_lshl_add_u32 v0, v8, 4, s93
	v_add_u32_e32 v1, 0x2000, v0
	v_ashrrev_i32_e32 v2, 31, v1
	v_lshrrev_b32_e32 v2, 22, v2
	v_add_u32_e32 v2, v1, v2
	v_ashrrev_i32_e32 v2, 10, v2
	v_mul_i32_i24_e32 v3, 0x400, v2
	v_sub_u32_e32 v1, v1, v3
	v_lshrrev_b32_e32 v3, 4, v1
	v_bitop3_b32 v1, v3, v1, 32 bitop3:0x6c
	v_ashrrev_i32_e32 v3, 31, v1
	v_lshrrev_b32_e32 v3, 26, v3
	v_add_u32_e32 v3, v1, v3
	v_ashrrev_i32_e32 v4, 6, v3
	v_and_b32_e32 v3, 0xffc0, v3
	v_sub_u32_e32 v1, v1, v3
	v_lshlrev_b32_e32 v5, 3, v2
	v_lshrrev_b16_e32 v3, 7, v1
	v_and_b32_e32 v5, -16, v5
	v_and_b32_e32 v3, 1, v3
	v_add_u32_e32 v5, v4, v5
	v_add_u16_e32 v1, v1, v3
	v_mov_b32_e32 v3, 1
	v_and_b32_e32 v4, 3, v4
	s_mov_b32 s10, 0x7fffe0
	v_lshrrev_b32_e32 v6, 2, v5
	v_lshlrev_b32_e32 v7, 1, v5
	v_lshlrev_b32_e32 v2, 5, v2
	v_ashrrev_i16_sdwa v1, v3, sext(v1) dst_sel:DWORD dst_unused:UNUSED_PAD src0_sel:DWORD src1_sel:BYTE_0
	v_and_or_b32 v4, v5, s10, v4
	v_and_b32_e32 v6, 4, v6
	v_and_b32_e32 v7, 24, v7
	v_and_b32_e32 v2, 32, v2
	v_bfe_i32 v1, v1, 0, 16
	v_or3_b32 v4, v4, v6, v7
	v_add_lshl_u32 v1, v2, v1, 1
	s_load_dwordx2 s[0:1], s[64:65], 0xc0
	v_lshl_add_u32 v128, v4, 9, v1
	v_lshl_add_u32 v130, v5, 9, v1
	v_ashrrev_i32_e32 v1, 31, v0
	v_lshrrev_b32_e32 v1, 22, v1
	v_add_u32_e32 v1, v0, v1
	v_ashrrev_i32_e32 v1, 10, v1
	s_ashr_i32 s36, s7, 31
	s_ashr_i32 s37, s40, 31
	v_mul_i32_i24_e32 v2, 0x400, v1
	s_waitcnt lgkmcnt(0)
	s_add_u32 s38, s0, 0x1f800000
	v_sub_u32_e32 v0, v0, v2
	s_addc_u32 s39, s1, 0
	v_lshrrev_b32_e32 v2, 4, v0
	s_add_u32 s41, s0, 0x1f500000
	v_bitop3_b32 v0, v2, v0, 32 bitop3:0x6c
	s_addc_u32 s42, s1, 0
	s_lshr_b32 s8, s37, 29
	v_ashrrev_i32_e32 v2, 31, v0
	s_add_i32 s8, s40, s8
	v_lshrrev_b32_e32 v2, 26, v2
	s_ashr_i32 s9, s8, 3
	s_and_b32 s8, s8, -8
	v_add_u32_e32 v2, v0, v2
	v_lshlrev_b32_e32 v5, 3, v1
	s_sub_i32 s8, s40, s8
	v_ashrrev_i32_e32 v4, 6, v2
	v_and_b32_e32 v5, -16, v5
	s_cmp_lt_i32 s8, 0
	v_add_u32_e32 v5, v4, v5
	v_and_b32_e32 v4, 3, v4
	s_movk_i32 s43, 0x49
	v_and_or_b32 v4, v5, s10, v4
	s_cselect_b32 s10, s43, 0x48
	s_mul_i32 s8, s8, s10
	s_add_i32 s8, s8, s9
	s_ashr_i32 s9, s8, 31
	s_lshr_b32 s9, s9, 25
	s_add_i32 s9, s8, s9
	s_ashr_i32 s10, s9, 7
	v_and_b32_e32 v2, 0xc0, v2
	s_lshl_b32 s10, s10, 3
	v_sub_u32_e32 v0, v0, v2
	s_sub_i32 s11, 36, s10
	v_lshlrev_b32_e32 v1, 5, v1
	v_ashrrev_i16_sdwa v0, v3, sext(v0) dst_sel:DWORD dst_unused:UNUSED_PAD src0_sel:DWORD src1_sel:BYTE_0
	s_min_u32 s11, s11, 8
	s_and_b32 s9, s9, 0xffffff80
	v_and_b32_e32 v1, 32, v1
	v_bfe_i32 v0, v0, 0, 16
	s_sub_i32 s15, s8, s9
	v_cvt_f32_ubyte0_e32 v2, s11
	v_add_lshl_u32 v0, v1, v0, 1
	v_cvt_f32_i32_e32 v1, s15
	v_rcp_iflag_f32_e32 v3, v2
	v_lshrrev_b32_e32 v6, 2, v5
	v_lshlrev_b32_e32 v7, 1, v5
	v_and_b32_e32 v6, 4, v6
	v_and_b32_e32 v7, 24, v7
	v_or3_b32 v4, v4, v6, v7
	v_lshl_add_u32 v132, v4, 9, v0
	v_lshl_add_u32 v134, v5, 9, v0
	v_mul_f32_e32 v0, v1, v3
	v_trunc_f32_e32 v0, v0
	v_fma_f32 v1, -v0, v2, v1
	v_cvt_i32_f32_e32 v0, v0
	s_ashr_i32 s8, s15, 30
	s_or_b32 s14, s8, 1
	v_cmp_ge_f32_e64 s[8:9], |v1|, v2
	s_and_b64 s[8:9], s[8:9], exec
	s_cselect_b32 s8, s14, 0
	v_readfirstlane_b32 s9, v0
	s_add_i32 s14, s9, s8
	s_mul_i32 s8, s14, s11
	s_sub_i32 s8, s15, s8
	s_sext_i32_i8 s8, s8
	s_add_i32 s24, s10, s8
	s_ashr_i32 s25, s24, 31
	s_bfe_i64 s[10:11], s[14:15], 0x80000
	s_lshl_b64 s[8:9], s[24:25], 17
	s_lshl_b64 s[10:11], s[10:11], 17
	s_add_u32 s26, s41, s10
	s_addc_u32 s27, s42, s11
	s_add_i32 s25, s93, 0
	s_add_i32 m0, s25, 0x10000
	v_mov_b32_e32 v133, 0
	global_load_lds_dwordx4 v132, s[26:27]
	s_add_i32 m0, s25, 0x12000
	s_add_u32 s28, s38, s8
	s_addc_u32 s29, s39, s9
	s_add_u32 s8, s26, 0x10000
	global_load_lds_dwordx4 v128, s[26:27]
	s_addc_u32 s9, s27, 0
	s_add_i32 m0, s25, 0x14000
	s_add_i32 s44, s25, 0x2000
	global_load_lds_dwordx4 v132, s[8:9]
	s_add_i32 m0, s25, 0x16000
	v_readlane_b32 s4, v250, 21
	global_load_lds_dwordx4 v128, s[8:9]
	s_mov_b32 m0, s25
	s_add_u32 s8, s28, 0x10000
	global_load_lds_dwordx4 v134, s[28:29]
	s_mov_b32 m0, s44
	s_addc_u32 s9, s29, 0
	s_add_i32 s45, s25, 0x4000
	global_load_lds_dwordx4 v130, s[28:29]
	s_mov_b32 m0, s45
	s_add_i32 s46, s25, 0x6000
	global_load_lds_dwordx4 v134, s[8:9]
	s_mov_b32 m0, s46
	v_mov_b32_e32 v129, v133
	global_load_lds_dwordx4 v130, s[8:9]
	v_mov_b32_e32 v135, v133
	v_mov_b32_e32 v131, v133
	v_readlane_b32 s5, v250, 22
	s_mov_b32 s47, 0
	v_lshl_add_u64 v[6:7], s[26:27], 0, v[132:133]
	v_lshl_add_u64 v[4:5], s[26:27], 0, v[128:129]
	v_lshl_add_u64 v[0:1], s[28:29], 0, v[134:135]
	s_and_b64 vcc, exec, s[4:5]
	v_lshl_add_u64 v[2:3], s[28:29], 0, v[130:131]
	s_cbranch_vccnz .LBB0_965
	s_barrier
.LBB0_965:
	s_add_u32 s8, s0, 0x45000000
	s_mov_b64 s[10:11], 0x80
	s_addc_u32 s9, s1, 0
	v_lshl_add_u64 v[6:7], v[6:7], 0, s[10:11]
	s_add_i32 m0, s25, 0x18000
	s_waitcnt vmcnt(2)
	s_barrier
	global_load_lds_dwordx4 v[6:7], off
	v_lshl_add_u64 v[4:5], v[4:5], 0, s[10:11]
	s_add_i32 m0, s25, 0x1a000
	s_add_i32 s48, s25, 0x8000
	s_add_i32 s49, s25, 0xa000
	global_load_lds_dwordx4 v[4:5], off
	v_lshl_add_u64 v[0:1], v[0:1], 0, s[10:11]
	s_mov_b32 m0, s48
	s_add_u32 s0, s26, 0x10080
	global_load_lds_dwordx4 v[0:1], off
	v_lshl_add_u64 v[0:1], v[2:3], 0, s[10:11]
	s_mov_b32 m0, s49
	s_addc_u32 s1, s27, 0
	global_load_lds_dwordx4 v[0:1], off
	v_lshl_add_u64 v[0:1], s[0:1], 0, v[132:133]
	s_add_i32 m0, s25, 0x1c000
	v_and_b32_e32 v4, 48, v8
	global_load_lds_dwordx4 v[0:1], off
	v_lshl_add_u64 v[0:1], s[0:1], 0, v[128:129]
	s_add_i32 m0, s25, 0x1e000
	v_readlane_b32 s0, v250, 13
	global_load_lds_dwordx4 v[0:1], off
	v_and_b32_e32 v0, 15, v8
	v_or_b32_e32 v140, s0, v0
	v_lshlrev_b32_e32 v3, 6, v140
	s_movk_i32 s0, 0x3c0
	v_ashrrev_i32_e32 v2, 6, v8
	v_and_or_b32 v3, v3, s0, v4
	v_readlane_b32 s0, v250, 14
	v_lshlrev_b32_e32 v6, 2, v140
	v_lshl_or_b32 v0, v0, 6, v4
	v_lshl_add_u32 v5, v2, 10, s0
	v_readlane_b32 s0, v250, 18
	v_lshlrev_b32_e32 v4, 2, v8
	v_ashrrev_i32_e32 v1, 1, v8
	v_and_b32_e32 v6, 32, v6
	v_add_lshl_u32 v2, v2, s0, 10
	v_and_b32_e32 v4, 32, v4
	s_waitcnt vmcnt(6)
	v_and_b32_e32 v1, -8, v1
	v_bitop3_b32 v3, v3, v5, v6 bitop3:0xde
	v_bitop3_b32 v141, v0, v2, v4 bitop3:0xde
	v_readlane_b32 s0, v250, 17
	s_add_i32 s50, 0, 0x10000
	s_add_i32 s51, 0, 0x14000
	s_sext_i32_i8 s53, s14
	v_add_u32_e32 v142, s0, v1
	v_mov_b32_e32 v136, s100
	v_mov_b32_e32 v137, 0
	v_mov_b32_e32 v138, s101
	v_mov_b32_e32 v139, 0
	v_add_u32_e32 v143, s50, v141
	v_add_u32_e32 v144, s51, v141
	v_add_u32_e32 v145, 0, v3
	s_mov_b32 s52, 0x160000
	s_barrier
	s_branch .LBB0_968

.LBB0_977:
	s_waitcnt vmcnt(0)
	s_barrier
	s_cmp_eq_u32 s98, 1
	s_cbranch_scc1 .Lp3_scan_resume
	s_mov_b32 s40, s99
